# P6 gate sigmoid: scalar f32 mul/add pairs replaced by packed f32 (v_pk_mul_f32 / v_pk_add_f32), numerically identical
# speedup vs baseline: 1.0036x; 1.0036x over previous
.LBB0_1290:
	s_and_b64 vcc, exec, s[26:27]
	s_cbranch_vccz .LBB0_1292
	s_mov_b32 s96, 0xbfb8aa3b
	s_mov_b32 s98, 0x437f0000
	v_pk_mul_f32 v[118:119], v[118:119], s[96:97] op_sel_hi:[1,0]
	s_nop 0
	v_exp_f32_e32 v118, v118
	v_exp_f32_e32 v119, v119
	v_pk_mul_f32 v[102:103], v[102:103], s[96:97] op_sel_hi:[1,0]
	s_nop 0
	v_exp_f32_e32 v102, v102
	v_pk_mul_f32 v[120:121], v[120:121], s[96:97] op_sel_hi:[1,0]
	v_exp_f32_e32 v103, v103
	v_pk_mul_f32 v[86:87], v[86:87], s[96:97] op_sel_hi:[1,0]
	s_nop 0
	v_exp_f32_e32 v120, v120
	s_nop 0
	s_nop 0
	v_exp_f32_e32 v86, v86
	v_pk_mul_f32 v[126:127], v[126:127], s[96:97] op_sel_hi:[1,0]
	v_exp_f32_e32 v121, v121
	v_pk_add_f32 v[118:119], v[118:119], 1.0 op_sel_hi:[1,0]
	v_rcp_f32_e32 v118, v118
	v_pk_mul_f32 v[110:111], v[110:111], s[96:97] op_sel_hi:[1,0]
	v_pk_mul_f32 v[104:105], v[104:105], s[96:97] op_sel_hi:[1,0]
	v_exp_f32_e32 v87, v87
	v_pk_mul_f32 v[70:71], v[70:71], s[96:97] op_sel_hi:[1,0]
	s_nop 0
	v_exp_f32_e32 v126, v126
	v_rcp_f32_e32 v119, v119
	s_nop 0
	v_exp_f32_e32 v110, v110
	s_nop 0
	v_exp_f32_e32 v104, v104
	s_nop 0
	v_pk_mul_f32 v[94:95], v[94:95], s[96:97] op_sel_hi:[1,0]
	v_pk_mul_f32 v[78:79], v[78:79], s[96:97] op_sel_hi:[1,0]
	s_nop 0
	v_exp_f32_e32 v70, v70
	v_pk_mul_f32 v[54:55], v[54:55], s[96:97] op_sel_hi:[1,0]
	v_exp_f32_e32 v127, v127
	v_exp_f32_e32 v111, v111
	v_exp_f32_e32 v105, v105
	v_pk_add_f32 v[102:103], v[102:103], 1.0 op_sel_hi:[1,0]
	v_rcp_f32_e32 v102, v102
	s_nop 0
	v_exp_f32_e32 v94, v94
	v_pk_mul_f32 v[88:89], v[88:89], s[96:97] op_sel_hi:[1,0]
	s_nop 0
	v_exp_f32_e32 v78, v78
	v_exp_f32_e32 v71, v71
	v_pk_mul_f32 v[62:63], v[62:63], s[96:97] op_sel_hi:[1,0]
	s_nop 0
	v_exp_f32_e32 v54, v54
	v_pk_mul_f32 v[46:47], v[46:47], s[96:97] op_sel_hi:[1,0]
	v_pk_mul_f32 v[38:39], v[38:39], s[96:97] op_sel_hi:[1,0]
	s_nop 0
	v_pk_mul_f32 v[114:115], v[114:115], s[96:97] op_sel_hi:[1,0]
	v_rcp_f32_e32 v103, v103
	v_exp_f32_e32 v95, v95
	s_nop 0
	v_exp_f32_e32 v88, v88
	s_nop 0
	v_exp_f32_e32 v79, v79
	s_nop 0
	v_exp_f32_e32 v62, v62
	v_exp_f32_e32 v55, v55
	s_nop 0
	v_exp_f32_e32 v46, v46
	s_nop 0
	v_exp_f32_e32 v38, v38
	v_pk_mul_f32 v[30:31], v[30:31], s[96:97] op_sel_hi:[1,0]
	v_pk_mul_f32 v[22:23], v[22:23], s[96:97] op_sel_hi:[1,0]
	v_pk_mul_f32 v[14:15], v[14:15], s[96:97] op_sel_hi:[1,0]
	v_pk_mul_f32 v[4:5], v[4:5], s[96:97] op_sel_hi:[1,0]
	v_pk_mul_f32 v[128:129], v[128:129], s[96:97] op_sel_hi:[1,0]
	v_pk_add_f32 v[120:121], v[120:121], 1.0 op_sel_hi:[1,0]
	v_rcp_f32_e32 v120, v120
	s_nop 0
	s_nop 0
	v_exp_f32_e32 v114, v114
	v_pk_mul_f32 v[112:113], v[112:113], s[96:97] op_sel_hi:[1,0]
	v_exp_f32_e32 v89, v89
	v_pk_add_f32 v[86:87], v[86:87], 1.0 op_sel_hi:[1,0]
	v_rcp_f32_e32 v86, v86
	v_pk_mul_f32 v[72:73], v[72:73], s[96:97] op_sel_hi:[1,0]
	v_exp_f32_e32 v63, v63
	v_exp_f32_e32 v47, v47
	v_exp_f32_e32 v39, v39
	s_nop 0
	v_exp_f32_e32 v30, v30
	s_nop 0
	v_exp_f32_e32 v22, v22
	s_nop 0
	v_exp_f32_e32 v14, v14
	s_nop 0
	v_exp_f32_e32 v4, v4
	s_nop 0
	v_exp_f32_e32 v128, v128
	s_nop 0
	v_rcp_f32_e32 v121, v121
	v_pk_mul_f32 v[118:119], v[118:119], s[98:99] op_sel_hi:[1,0]
	v_cvt_pk_u8_f32 v118, v118, 0, 0
	v_pk_mul_f32 v[116:117], v[116:117], s[96:97] op_sel_hi:[1,0]
	v_exp_f32_e32 v115, v115
	s_nop 0
	v_exp_f32_e32 v112, v112
	s_nop 0
	s_nop 0
	v_pk_mul_f32 v[98:99], v[98:99], s[96:97] op_sel_hi:[1,0]
	v_pk_mul_f32 v[96:97], v[96:97], s[96:97] op_sel_hi:[1,0]
	v_rcp_f32_e32 v87, v87
	v_pk_mul_f32 v[80:81], v[80:81], s[96:97] op_sel_hi:[1,0]
	s_nop 0
	v_exp_f32_e32 v72, v72
	s_nop 0
	v_pk_mul_f32 v[56:57], v[56:57], s[96:97] op_sel_hi:[1,0]
	v_exp_f32_e32 v31, v31
	v_exp_f32_e32 v23, v23
	v_exp_f32_e32 v15, v15
	v_exp_f32_e32 v5, v5
	v_exp_f32_e32 v129, v129
	v_pk_add_f32 v[126:127], v[126:127], 1.0 op_sel_hi:[1,0]
	v_rcp_f32_e32 v126, v126
	v_cvt_pk_u8_f32 v118, v119, 1, v118
	s_nop 0
	v_exp_f32_e32 v119, v116
	v_exp_f32_e32 v113, v113
	v_pk_add_f32 v[110:111], v[110:111], 1.0 op_sel_hi:[1,0]
	v_rcp_f32_e32 v110, v110
	v_pk_add_f32 v[104:105], v[104:105], 1.0 op_sel_hi:[1,0]
	v_rcp_f32_e32 v104, v104
	s_nop 0
	s_nop 0
	v_exp_f32_e32 v98, v98
	s_nop 0
	v_exp_f32_e32 v96, v96
	s_nop 0
	s_nop 0
	v_exp_f32_e32 v80, v80
	s_nop 0
	v_exp_f32_e32 v73, v73
	v_pk_add_f32 v[70:71], v[70:71], 1.0 op_sel_hi:[1,0]
	v_rcp_f32_e32 v70, v70
	v_pk_mul_f32 v[64:65], v[64:65], s[96:97] op_sel_hi:[1,0]
	s_nop 0
	v_exp_f32_e32 v56, v56
	s_nop 0
	v_pk_mul_f32 v[48:49], v[48:49], s[96:97] op_sel_hi:[1,0]
	v_pk_mul_f32 v[40:41], v[40:41], s[96:97] op_sel_hi:[1,0]
	v_rcp_f32_e32 v127, v127
	v_exp_f32_e32 v117, v117
	v_rcp_f32_e32 v111, v111
	v_rcp_f32_e32 v105, v105
	v_pk_mul_f32 v[102:103], v[102:103], s[98:99] op_sel_hi:[1,0]
	v_cvt_pk_u8_f32 v102, v102, 0, 0
	v_pk_mul_f32 v[100:101], v[100:101], s[96:97] op_sel_hi:[1,0]
	v_exp_f32_e32 v99, v99
	v_exp_f32_e32 v97, v97
	v_pk_add_f32 v[94:95], v[94:95], 1.0 op_sel_hi:[1,0]
	v_rcp_f32_e32 v94, v94
	s_nop 0
	v_pk_mul_f32 v[82:83], v[82:83], s[96:97] op_sel_hi:[1,0]
	v_exp_f32_e32 v81, v81
	v_pk_add_f32 v[78:79], v[78:79], 1.0 op_sel_hi:[1,0]
	v_rcp_f32_e32 v78, v78
	v_rcp_f32_e32 v71, v71
	s_nop 0
	v_exp_f32_e32 v64, v64
	s_nop 0
	v_exp_f32_e32 v57, v57
	v_pk_add_f32 v[54:55], v[54:55], 1.0 op_sel_hi:[1,0]
	v_rcp_f32_e32 v54, v54
	s_nop 0
	v_exp_f32_e32 v48, v48
	s_nop 0
	s_nop 0
	v_exp_f32_e32 v40, v40
	s_nop 0
	v_pk_mul_f32 v[32:33], v[32:33], s[96:97] op_sel_hi:[1,0]
	v_pk_mul_f32 v[24:25], v[24:25], s[96:97] op_sel_hi:[1,0]
	v_pk_mul_f32 v[16:17], v[16:17], s[96:97] op_sel_hi:[1,0]
	v_pk_mul_f32 v[6:7], v[6:7], s[96:97] op_sel_hi:[1,0]
	s_nop 0
	s_nop 0
	v_cvt_pk_u8_f32 v102, v103, 1, v102
	s_nop 0
	v_exp_f32_e32 v103, v100
	v_rcp_f32_e32 v95, v95
	v_pk_add_f32 v[88:89], v[88:89], 1.0 op_sel_hi:[1,0]
	v_rcp_f32_e32 v88, v88
	s_nop 0
	s_nop 0
	v_exp_f32_e32 v82, v82
	v_rcp_f32_e32 v79, v79
	v_exp_f32_e32 v65, v65
	v_pk_add_f32 v[62:63], v[62:63], 1.0 op_sel_hi:[1,0]
	v_rcp_f32_e32 v62, v62
	v_rcp_f32_e32 v55, v55
	v_exp_f32_e32 v49, v49
	v_pk_add_f32 v[46:47], v[46:47], 1.0 op_sel_hi:[1,0]
	v_rcp_f32_e32 v46, v46
	v_exp_f32_e32 v41, v41
	v_pk_add_f32 v[38:39], v[38:39], 1.0 op_sel_hi:[1,0]
	v_rcp_f32_e32 v38, v38
	s_nop 0
	v_exp_f32_e32 v32, v32
	s_nop 0
	s_nop 0
	v_exp_f32_e32 v24, v24
	s_nop 0
	s_nop 0
	v_exp_f32_e32 v16, v16
	s_nop 0
	s_nop 0
	v_exp_f32_e32 v6, v6
	s_nop 0
	s_nop 0
	v_pk_mul_f32 v[122:123], v[122:123], s[96:97] op_sel_hi:[1,0]
	v_pk_mul_f32 v[120:121], v[120:121], s[98:99] op_sel_hi:[1,0]
	v_cvt_pk_u8_f32 v118, v120, 2, v118
	v_pk_add_f32 v[114:115], v[114:115], 1.0 op_sel_hi:[1,0]
	v_rcp_f32_e32 v114, v114
	s_nop 0
	v_pk_mul_f32 v[106:107], v[106:107], s[96:97] op_sel_hi:[1,0]
	v_exp_f32_e32 v101, v101
	v_rcp_f32_e32 v89, v89
	v_pk_mul_f32 v[86:87], v[86:87], s[98:99] op_sel_hi:[1,0]
	v_cvt_pk_u8_f32 v86, v86, 0, 0
	v_pk_mul_f32 v[84:85], v[84:85], s[96:97] op_sel_hi:[1,0]
	v_exp_f32_e32 v83, v83
	s_nop 0
	v_pk_mul_f32 v[66:67], v[66:67], s[96:97] op_sel_hi:[1,0]
	v_rcp_f32_e32 v63, v63
	v_rcp_f32_e32 v47, v47
	v_rcp_f32_e32 v39, v39
	v_exp_f32_e32 v33, v33
	v_pk_add_f32 v[30:31], v[30:31], 1.0 op_sel_hi:[1,0]
	v_rcp_f32_e32 v30, v30
	v_exp_f32_e32 v25, v25
	v_pk_add_f32 v[22:23], v[22:23], 1.0 op_sel_hi:[1,0]
	v_rcp_f32_e32 v22, v22
	v_exp_f32_e32 v17, v17
	v_pk_add_f32 v[14:15], v[14:15], 1.0 op_sel_hi:[1,0]
	v_rcp_f32_e32 v14, v14
	v_exp_f32_e32 v7, v7
	v_pk_add_f32 v[4:5], v[4:5], 1.0 op_sel_hi:[1,0]
	v_rcp_f32_e32 v4, v4
	v_pk_add_f32 v[128:129], v[128:129], 1.0 op_sel_hi:[1,0]
	v_rcp_f32_e32 v128, v128
	s_nop 0
	s_nop 0
	v_exp_f32_e32 v122, v122
	v_cvt_pk_u8_f32 v116, v121, 3, v118
	v_add_f32_e32 v118, 1.0, v119
	v_rcp_f32_e32 v115, v115
	v_pk_add_f32 v[112:113], v[112:113], 1.0 op_sel_hi:[1,0]
	v_rcp_f32_e32 v112, v112
	s_nop 0
	s_nop 0
	v_exp_f32_e32 v106, v106
	s_nop 0
	s_nop 0
	s_nop 0
	v_pk_mul_f32 v[90:91], v[90:91], s[96:97] op_sel_hi:[1,0]
	v_cvt_pk_u8_f32 v86, v87, 1, v86
	s_nop 0
	v_exp_f32_e32 v87, v84
	s_nop 0
	v_pk_mul_f32 v[74:75], v[74:75], s[96:97] op_sel_hi:[1,0]
	v_pk_add_f32 v[72:73], v[72:73], 1.0 op_sel_hi:[1,0]
	v_rcp_f32_e32 v72, v72
	s_nop 0
	s_nop 0
	v_exp_f32_e32 v66, v66
	s_nop 0
	v_pk_mul_f32 v[50:51], v[50:51], s[96:97] op_sel_hi:[1,0]
	v_rcp_f32_e32 v31, v31
	v_rcp_f32_e32 v23, v23
	v_rcp_f32_e32 v15, v15
	v_rcp_f32_e32 v5, v5
	v_rcp_f32_e32 v129, v129
	v_pk_mul_f32 v[126:127], v[126:127], s[98:99] op_sel_hi:[1,0]
	v_cvt_pk_u8_f32 v126, v126, 0, 0
	v_pk_mul_f32 v[124:125], v[124:125], s[96:97] op_sel_hi:[1,0]
	v_exp_f32_e32 v123, v123
	v_add_f32_e32 v117, 1.0, v117
	v_rcp_f32_e32 v118, v118
	v_rcp_f32_e32 v113, v113
	v_pk_mul_f32 v[110:111], v[110:111], s[98:99] op_sel_hi:[1,0]
	v_cvt_pk_u8_f32 v110, v110, 0, 0
	v_pk_mul_f32 v[108:109], v[108:109], s[96:97] op_sel_hi:[1,0]
	v_exp_f32_e32 v107, v107
	v_pk_mul_f32 v[104:105], v[104:105], s[98:99] op_sel_hi:[1,0]
	v_cvt_pk_u8_f32 v102, v104, 2, v102
	v_pk_add_f32 v[98:99], v[98:99], 1.0 op_sel_hi:[1,0]
	v_rcp_f32_e32 v98, v98
	v_pk_add_f32 v[96:97], v[96:97], 1.0 op_sel_hi:[1,0]
	v_rcp_f32_e32 v96, v96
	s_nop 0
	s_nop 0
	v_exp_f32_e32 v90, v90
	v_exp_f32_e32 v85, v85
	v_pk_add_f32 v[80:81], v[80:81], 1.0 op_sel_hi:[1,0]
	v_rcp_f32_e32 v80, v80
	s_nop 0
	s_nop 0
	v_exp_f32_e32 v74, v74
	v_rcp_f32_e32 v73, v73
	v_pk_mul_f32 v[70:71], v[70:71], s[98:99] op_sel_hi:[1,0]
	v_cvt_pk_u8_f32 v70, v70, 0, 0
	v_pk_mul_f32 v[68:69], v[68:69], s[96:97] op_sel_hi:[1,0]
	v_exp_f32_e32 v67, v67
	s_nop 0
	v_pk_mul_f32 v[58:59], v[58:59], s[96:97] op_sel_hi:[1,0]
	v_pk_add_f32 v[56:57], v[56:57], 1.0 op_sel_hi:[1,0]
	v_rcp_f32_e32 v56, v56
	s_nop 0
	s_nop 0
	v_exp_f32_e32 v50, v50
	s_nop 0
	v_pk_mul_f32 v[42:43], v[42:43], s[96:97] op_sel_hi:[1,0]
	s_nop 0
	v_pk_mul_f32 v[34:35], v[34:35], s[96:97] op_sel_hi:[1,0]
	v_cvt_pk_u8_f32 v126, v127, 1, v126
	s_nop 0
	v_exp_f32_e32 v127, v124
	v_rcp_f32_e32 v117, v117
	v_cvt_pk_u8_f32 v110, v111, 1, v110
	s_nop 0
	v_exp_f32_e32 v111, v108
	v_cvt_pk_u8_f32 v100, v105, 3, v102
	v_add_f32_e32 v102, 1.0, v103
	v_rcp_f32_e32 v99, v99
	v_rcp_f32_e32 v97, v97
	v_pk_mul_f32 v[94:95], v[94:95], s[98:99] op_sel_hi:[1,0]
	v_cvt_pk_u8_f32 v94, v94, 0, 0
	v_pk_mul_f32 v[92:93], v[92:93], s[96:97] op_sel_hi:[1,0]
	v_exp_f32_e32 v91, v91
	s_nop 0
	s_nop 0
	v_rcp_f32_e32 v81, v81
	v_pk_mul_f32 v[78:79], v[78:79], s[98:99] op_sel_hi:[1,0]
	v_cvt_pk_u8_f32 v78, v78, 0, 0
	v_pk_mul_f32 v[76:77], v[76:77], s[96:97] op_sel_hi:[1,0]
	v_exp_f32_e32 v75, v75
	v_cvt_pk_u8_f32 v70, v71, 1, v70
	s_nop 0
	v_exp_f32_e32 v71, v68
	v_pk_add_f32 v[64:65], v[64:65], 1.0 op_sel_hi:[1,0]
	v_rcp_f32_e32 v64, v64
	s_nop 0
	s_nop 0
	v_exp_f32_e32 v58, v58
	v_rcp_f32_e32 v57, v57
	v_pk_mul_f32 v[54:55], v[54:55], s[98:99] op_sel_hi:[1,0]
	v_cvt_pk_u8_f32 v54, v54, 0, 0
	v_pk_mul_f32 v[52:53], v[52:53], s[96:97] op_sel_hi:[1,0]
	v_exp_f32_e32 v51, v51
	v_pk_add_f32 v[48:49], v[48:49], 1.0 op_sel_hi:[1,0]
	v_rcp_f32_e32 v48, v48
	s_nop 0
	s_nop 0
	v_exp_f32_e32 v42, v42
	v_pk_add_f32 v[40:41], v[40:41], 1.0 op_sel_hi:[1,0]
	v_rcp_f32_e32 v40, v40
	s_nop 0
	s_nop 0
	v_exp_f32_e32 v34, v34
	s_nop 0
	v_pk_mul_f32 v[26:27], v[26:27], s[96:97] op_sel_hi:[1,0]
	s_nop 0
	v_pk_mul_f32 v[18:19], v[18:19], s[96:97] op_sel_hi:[1,0]
	s_nop 0
	v_pk_mul_f32 v[10:11], v[10:11], s[96:97] op_sel_hi:[1,0]
	s_nop 0
	v_pk_mul_f32 v[0:1], v[0:1], s[96:97] op_sel_hi:[1,0]
	v_exp_f32_e32 v125, v125
	s_nop 0
	v_exp_f32_e32 v109, v109
	v_add_f32_e32 v101, 1.0, v101
	v_rcp_f32_e32 v102, v102
	v_cvt_pk_u8_f32 v94, v95, 1, v94
	s_nop 0
	v_exp_f32_e32 v95, v92
	v_pk_mul_f32 v[88:89], v[88:89], s[98:99] op_sel_hi:[1,0]
	v_cvt_pk_u8_f32 v86, v88, 2, v86
	v_pk_add_f32 v[82:83], v[82:83], 1.0 op_sel_hi:[1,0]
	v_rcp_f32_e32 v82, v82
	v_cvt_pk_u8_f32 v78, v79, 1, v78
	s_nop 0
	v_exp_f32_e32 v79, v76
	v_exp_f32_e32 v69, v69
	v_rcp_f32_e32 v65, v65
	v_pk_mul_f32 v[62:63], v[62:63], s[98:99] op_sel_hi:[1,0]
	v_cvt_pk_u8_f32 v62, v62, 0, 0
	v_pk_mul_f32 v[60:61], v[60:61], s[96:97] op_sel_hi:[1,0]
	v_exp_f32_e32 v59, v59
	v_cvt_pk_u8_f32 v54, v55, 1, v54
	s_nop 0
	v_exp_f32_e32 v55, v52
	v_rcp_f32_e32 v49, v49
	v_pk_mul_f32 v[46:47], v[46:47], s[98:99] op_sel_hi:[1,0]
	v_cvt_pk_u8_f32 v46, v46, 0, 0
	v_pk_mul_f32 v[44:45], v[44:45], s[96:97] op_sel_hi:[1,0]
	v_exp_f32_e32 v43, v43
	v_rcp_f32_e32 v41, v41
	v_pk_mul_f32 v[38:39], v[38:39], s[98:99] op_sel_hi:[1,0]
	v_cvt_pk_u8_f32 v38, v38, 0, 0
	v_pk_mul_f32 v[36:37], v[36:37], s[96:97] op_sel_hi:[1,0]
	v_exp_f32_e32 v35, v35
	v_pk_add_f32 v[32:33], v[32:33], 1.0 op_sel_hi:[1,0]
	v_rcp_f32_e32 v32, v32
	s_nop 0
	s_nop 0
	v_exp_f32_e32 v26, v26
	v_pk_add_f32 v[24:25], v[24:25], 1.0 op_sel_hi:[1,0]
	v_rcp_f32_e32 v24, v24
	s_nop 0
	s_nop 0
	v_exp_f32_e32 v18, v18
	v_pk_add_f32 v[16:17], v[16:17], 1.0 op_sel_hi:[1,0]
	v_rcp_f32_e32 v16, v16
	s_nop 0
	s_nop 0
	v_exp_f32_e32 v10, v10
	v_pk_add_f32 v[6:7], v[6:7], 1.0 op_sel_hi:[1,0]
	v_rcp_f32_e32 v6, v6
	s_nop 0
	s_nop 0
	v_exp_f32_e32 v0, v0
	s_nop 0
	s_nop 0
	v_pk_mul_f32 v[114:115], v[114:115], s[98:99] op_sel_hi:[1,0]
	v_cvt_pk_u8_f32 v114, v114, 0, 0
	s_nop 0
	s_nop 0
	v_rcp_f32_e32 v101, v101
	v_exp_f32_e32 v93, v93
	v_cvt_pk_u8_f32 v84, v89, 3, v86
	v_add_f32_e32 v86, 1.0, v87
	v_rcp_f32_e32 v83, v83
	v_exp_f32_e32 v77, v77
	s_nop 0
	s_nop 0
	v_cvt_pk_u8_f32 v62, v63, 1, v62
	s_nop 0
	v_exp_f32_e32 v63, v60
	v_exp_f32_e32 v53, v53
	v_cvt_pk_u8_f32 v46, v47, 1, v46
	s_nop 0
	v_exp_f32_e32 v47, v44
	v_cvt_pk_u8_f32 v38, v39, 1, v38
	s_nop 0
	v_exp_f32_e32 v39, v36
	v_rcp_f32_e32 v33, v33
	v_pk_mul_f32 v[30:31], v[30:31], s[98:99] op_sel_hi:[1,0]
	v_cvt_pk_u8_f32 v30, v30, 0, 0
	v_pk_mul_f32 v[28:29], v[28:29], s[96:97] op_sel_hi:[1,0]
	v_exp_f32_e32 v27, v27
	v_rcp_f32_e32 v25, v25
	v_pk_mul_f32 v[22:23], v[22:23], s[98:99] op_sel_hi:[1,0]
	v_cvt_pk_u8_f32 v22, v22, 0, 0
	v_pk_mul_f32 v[20:21], v[20:21], s[96:97] op_sel_hi:[1,0]
	v_exp_f32_e32 v19, v19
	v_rcp_f32_e32 v17, v17
	v_pk_mul_f32 v[14:15], v[14:15], s[98:99] op_sel_hi:[1,0]
	v_cvt_pk_u8_f32 v14, v14, 0, 0
	v_pk_mul_f32 v[12:13], v[12:13], s[96:97] op_sel_hi:[1,0]
	v_exp_f32_e32 v11, v11
	v_rcp_f32_e32 v7, v7
	v_pk_mul_f32 v[4:5], v[4:5], s[98:99] op_sel_hi:[1,0]
	v_cvt_pk_u8_f32 v4, v4, 0, 0
	v_pk_mul_f32 v[2:3], v[2:3], s[96:97] op_sel_hi:[1,0]
	v_exp_f32_e32 v1, v1
	v_pk_mul_f32 v[128:129], v[128:129], s[98:99] op_sel_hi:[1,0]
	v_cvt_pk_u8_f32 v126, v128, 2, v126
	v_pk_add_f32 v[122:123], v[122:123], 1.0 op_sel_hi:[1,0]
	v_rcp_f32_e32 v122, v122
	v_mul_f32_e32 v118, 0x437f0000, v118
	v_cvt_pk_u8_f32 v114, v115, 1, v114
	v_pk_mul_f32 v[112:113], v[112:113], s[98:99] op_sel_hi:[1,0]
	v_cvt_pk_u8_f32 v110, v112, 2, v110
	v_pk_add_f32 v[106:107], v[106:107], 1.0 op_sel_hi:[1,0]
	v_rcp_f32_e32 v106, v106
	s_nop 0
	s_nop 0
	s_nop 0
	v_add_f32_e32 v85, 1.0, v85
	v_rcp_f32_e32 v86, v86
	s_nop 0
	s_nop 0
	v_pk_mul_f32 v[72:73], v[72:73], s[98:99] op_sel_hi:[1,0]
	v_cvt_pk_u8_f32 v70, v72, 2, v70
	v_pk_add_f32 v[66:67], v[66:67], 1.0 op_sel_hi:[1,0]
	v_rcp_f32_e32 v66, v66
	v_exp_f32_e32 v61, v61
	s_nop 0
	s_nop 0
	v_exp_f32_e32 v45, v45
	v_exp_f32_e32 v37, v37
	v_cvt_pk_u8_f32 v30, v31, 1, v30
	s_nop 0
	v_exp_f32_e32 v31, v28
	v_cvt_pk_u8_f32 v22, v23, 1, v22
	s_nop 0
	v_exp_f32_e32 v23, v20
	v_cvt_pk_u8_f32 v14, v15, 1, v14
	s_nop 0
	v_exp_f32_e32 v15, v12
	v_cvt_pk_u8_f32 v4, v5, 1, v4
	s_nop 0
	v_exp_f32_e32 v5, v2
	v_cvt_pk_u8_f32 v124, v129, 3, v126
	v_add_f32_e32 v126, 1.0, v127
	v_rcp_f32_e32 v123, v123
	v_mul_f32_e32 v117, 0x437f0000, v117
	v_cvt_pk_u8_f32 v114, v118, 2, v114
	s_movk_i32 s24, 0x2000
	v_cvt_pk_u8_f32 v108, v113, 3, v110
	v_add_f32_e32 v110, 1.0, v111
	v_rcp_f32_e32 v107, v107
	v_pk_mul_f32 v[98:99], v[98:99], s[98:99] op_sel_hi:[1,0]
	v_cvt_pk_u8_f32 v98, v98, 0, 0
	v_pk_mul_f32 v[96:97], v[96:97], s[98:99] op_sel_hi:[1,0]
	v_cvt_pk_u8_f32 v94, v96, 2, v94
	v_pk_add_f32 v[90:91], v[90:91], 1.0 op_sel_hi:[1,0]
	v_rcp_f32_e32 v90, v90
	v_rcp_f32_e32 v85, v85
	v_pk_mul_f32 v[80:81], v[80:81], s[98:99] op_sel_hi:[1,0]
	v_cvt_pk_u8_f32 v78, v80, 2, v78
	v_pk_add_f32 v[74:75], v[74:75], 1.0 op_sel_hi:[1,0]
	v_rcp_f32_e32 v74, v74
	v_cvt_pk_u8_f32 v68, v73, 3, v70
	v_add_f32_e32 v70, 1.0, v71
	v_rcp_f32_e32 v67, v67
	s_nop 0
	s_nop 0
	v_pk_mul_f32 v[56:57], v[56:57], s[98:99] op_sel_hi:[1,0]
	v_cvt_pk_u8_f32 v54, v56, 2, v54
	v_pk_add_f32 v[50:51], v[50:51], 1.0 op_sel_hi:[1,0]
	v_rcp_f32_e32 v50, v50
	s_nop 0
	s_nop 0
	s_nop 0
	s_nop 0
	v_exp_f32_e32 v29, v29
	v_exp_f32_e32 v21, v21
	v_exp_f32_e32 v13, v13
	v_exp_f32_e32 v3, v3
	v_add_f32_e32 v125, 1.0, v125
	v_rcp_f32_e32 v126, v126
	v_cvt_pk_u8_f32 v117, v117, 3, v114
	v_add_co_u32_e32 v114, vcc, s24, v188
	v_add_f32_e32 v109, 1.0, v109
	v_rcp_f32_e32 v110, v110
	v_mul_f32_e32 v102, 0x437f0000, v102
	v_cvt_pk_u8_f32 v98, v99, 1, v98
	v_cvt_pk_u8_f32 v92, v97, 3, v94
	v_add_f32_e32 v94, 1.0, v95
	v_rcp_f32_e32 v91, v91
	s_nop 0
	v_cvt_pk_u8_f32 v76, v81, 3, v78
	v_add_f32_e32 v78, 1.0, v79
	v_rcp_f32_e32 v75, v75
	v_add_f32_e32 v69, 1.0, v69
	v_rcp_f32_e32 v70, v70
	v_pk_mul_f32 v[64:65], v[64:65], s[98:99] op_sel_hi:[1,0]
	v_cvt_pk_u8_f32 v62, v64, 2, v62
	v_pk_add_f32 v[58:59], v[58:59], 1.0 op_sel_hi:[1,0]
	v_rcp_f32_e32 v58, v58
	v_cvt_pk_u8_f32 v52, v57, 3, v54
	v_add_f32_e32 v54, 1.0, v55
	v_rcp_f32_e32 v51, v51
	v_pk_mul_f32 v[48:49], v[48:49], s[98:99] op_sel_hi:[1,0]
	v_cvt_pk_u8_f32 v46, v48, 2, v46
	v_pk_add_f32 v[42:43], v[42:43], 1.0 op_sel_hi:[1,0]
	v_rcp_f32_e32 v42, v42
	v_pk_mul_f32 v[40:41], v[40:41], s[98:99] op_sel_hi:[1,0]
	v_cvt_pk_u8_f32 v38, v40, 2, v38
	v_pk_add_f32 v[34:35], v[34:35], 1.0 op_sel_hi:[1,0]
	v_rcp_f32_e32 v34, v34
	s_nop 0
	s_nop 0
	s_nop 0
	s_nop 0
	s_nop 0
	s_nop 0
	s_nop 0
	s_nop 0
	v_rcp_f32_e32 v125, v125
	v_addc_co_u32_e32 v115, vcc, 0, v189, vcc
	v_rcp_f32_e32 v109, v109
	v_mul_f32_e32 v101, 0x437f0000, v101
	v_cvt_pk_u8_f32 v98, v102, 2, v98
	s_movk_i32 s24, 0x4000
	v_add_f32_e32 v93, 1.0, v93
	v_rcp_f32_e32 v94, v94
	v_pk_mul_f32 v[82:83], v[82:83], s[98:99] op_sel_hi:[1,0]
	v_cvt_pk_u8_f32 v82, v82, 0, 0
	v_add_f32_e32 v77, 1.0, v77
	v_rcp_f32_e32 v78, v78
	v_rcp_f32_e32 v69, v69
	v_cvt_pk_u8_f32 v60, v65, 3, v62
	v_add_f32_e32 v62, 1.0, v63
	v_rcp_f32_e32 v59, v59
	v_add_f32_e32 v53, 1.0, v53
	v_rcp_f32_e32 v54, v54
	v_cvt_pk_u8_f32 v44, v49, 3, v46
	v_add_f32_e32 v46, 1.0, v47
	v_rcp_f32_e32 v43, v43
	v_cvt_pk_u8_f32 v36, v41, 3, v38
	v_add_f32_e32 v38, 1.0, v39
	v_rcp_f32_e32 v35, v35
	v_pk_mul_f32 v[32:33], v[32:33], s[98:99] op_sel_hi:[1,0]
	v_cvt_pk_u8_f32 v30, v32, 2, v30
	v_pk_add_f32 v[26:27], v[26:27], 1.0 op_sel_hi:[1,0]
	v_rcp_f32_e32 v26, v26
	v_pk_mul_f32 v[24:25], v[24:25], s[98:99] op_sel_hi:[1,0]
	v_cvt_pk_u8_f32 v22, v24, 2, v22
	v_pk_add_f32 v[18:19], v[18:19], 1.0 op_sel_hi:[1,0]
	v_rcp_f32_e32 v18, v18
	v_pk_mul_f32 v[16:17], v[16:17], s[98:99] op_sel_hi:[1,0]
	v_cvt_pk_u8_f32 v14, v16, 2, v14
	v_pk_add_f32 v[10:11], v[10:11], 1.0 op_sel_hi:[1,0]
	v_rcp_f32_e32 v10, v10
	v_pk_mul_f32 v[6:7], v[6:7], s[98:99] op_sel_hi:[1,0]
	v_cvt_pk_u8_f32 v4, v6, 2, v4
	v_pk_add_f32 v[0:1], v[0:1], 1.0 op_sel_hi:[1,0]
	v_rcp_f32_e32 v0, v0
	s_nop 0
	s_nop 0
	v_cvt_pk_u8_f32 v101, v101, 3, v98
	v_add_co_u32_e32 v98, vcc, s24, v188
	v_rcp_f32_e32 v93, v93
	v_mul_f32_e32 v86, 0x437f0000, v86
	v_cvt_pk_u8_f32 v82, v83, 1, v82
	v_rcp_f32_e32 v77, v77
	s_nop 0
	v_add_f32_e32 v61, 1.0, v61
	v_rcp_f32_e32 v62, v62
	v_rcp_f32_e32 v53, v53
	v_add_f32_e32 v45, 1.0, v45
	v_rcp_f32_e32 v46, v46
	v_add_f32_e32 v37, 1.0, v37
	v_rcp_f32_e32 v38, v38
	v_cvt_pk_u8_f32 v28, v33, 3, v30
	v_add_f32_e32 v30, 1.0, v31
	v_rcp_f32_e32 v27, v27
	v_cvt_pk_u8_f32 v20, v25, 3, v22
	v_add_f32_e32 v22, 1.0, v23
	v_rcp_f32_e32 v19, v19
	v_cvt_pk_u8_f32 v12, v17, 3, v14
	v_add_f32_e32 v14, 1.0, v15
	v_rcp_f32_e32 v11, v11
	v_cvt_pk_u8_f32 v2, v7, 3, v4
	v_add_f32_e32 v4, 1.0, v5
	v_rcp_f32_e32 v1, v1
	v_pk_mul_f32 v[122:123], v[122:123], s[98:99] op_sel_hi:[1,0]
	v_cvt_pk_u8_f32 v122, v122, 0, 0
	v_pk_mul_f32 v[106:107], v[106:107], s[98:99] op_sel_hi:[1,0]
	v_cvt_pk_u8_f32 v106, v106, 0, 0
	v_addc_co_u32_e32 v99, vcc, 0, v189, vcc
	s_nop 0
	v_mul_f32_e32 v85, 0x437f0000, v85
	v_cvt_pk_u8_f32 v82, v86, 2, v82
	s_movk_i32 s24, 0x6000
	s_nop 0
	v_pk_mul_f32 v[66:67], v[66:67], s[98:99] op_sel_hi:[1,0]
	v_cvt_pk_u8_f32 v66, v66, 0, 0
	v_rcp_f32_e32 v61, v61
	s_nop 0
	v_rcp_f32_e32 v45, v45
	v_rcp_f32_e32 v37, v37
	v_add_f32_e32 v29, 1.0, v29
	v_rcp_f32_e32 v30, v30
	v_add_f32_e32 v21, 1.0, v21
	v_rcp_f32_e32 v22, v22
	v_add_f32_e32 v13, 1.0, v13
	v_rcp_f32_e32 v14, v14
	v_add_f32_e32 v3, 1.0, v3
	v_rcp_f32_e32 v4, v4
	v_mul_f32_e32 v126, 0x437f0000, v126
	v_cvt_pk_u8_f32 v122, v123, 1, v122
	v_mul_f32_e32 v110, 0x437f0000, v110
	v_cvt_pk_u8_f32 v106, v107, 1, v106
	v_pk_mul_f32 v[90:91], v[90:91], s[98:99] op_sel_hi:[1,0]
	v_cvt_pk_u8_f32 v90, v90, 0, 0
	v_cvt_pk_u8_f32 v85, v85, 3, v82
	v_add_co_u32_e32 v82, vcc, s24, v188
	v_pk_mul_f32 v[74:75], v[74:75], s[98:99] op_sel_hi:[1,0]
	v_cvt_pk_u8_f32 v74, v74, 0, 0
	v_mul_f32_e32 v70, 0x437f0000, v70
	v_cvt_pk_u8_f32 v66, v67, 1, v66
	s_nop 0
	v_pk_mul_f32 v[50:51], v[50:51], s[98:99] op_sel_hi:[1,0]
	v_cvt_pk_u8_f32 v50, v50, 0, 0
	s_nop 0
	s_nop 0
	v_rcp_f32_e32 v29, v29
	v_rcp_f32_e32 v21, v21
	v_rcp_f32_e32 v13, v13
	v_rcp_f32_e32 v3, v3
	v_mul_f32_e32 v125, 0x437f0000, v125
	v_cvt_pk_u8_f32 v122, v126, 2, v122
	v_mul_f32_e32 v109, 0x437f0000, v109
	v_cvt_pk_u8_f32 v106, v110, 2, v106
	v_mul_f32_e32 v94, 0x437f0000, v94
	v_cvt_pk_u8_f32 v90, v91, 1, v90
	v_addc_co_u32_e32 v83, vcc, 0, v189, vcc
	v_mul_f32_e32 v78, 0x437f0000, v78
	v_cvt_pk_u8_f32 v74, v75, 1, v74
	v_mul_f32_e32 v69, 0x437f0000, v69
	v_cvt_pk_u8_f32 v66, v70, 2, v66
	s_mov_b32 s24, 0x8000
	v_pk_mul_f32 v[58:59], v[58:59], s[98:99] op_sel_hi:[1,0]
	v_cvt_pk_u8_f32 v58, v58, 0, 0
	v_mul_f32_e32 v54, 0x437f0000, v54
	v_cvt_pk_u8_f32 v50, v51, 1, v50
	v_pk_mul_f32 v[42:43], v[42:43], s[98:99] op_sel_hi:[1,0]
	v_cvt_pk_u8_f32 v42, v42, 0, 0
	v_pk_mul_f32 v[34:35], v[34:35], s[98:99] op_sel_hi:[1,0]
	v_cvt_pk_u8_f32 v34, v34, 0, 0
	s_nop 0
	s_nop 0
	s_nop 0
	s_nop 0
	v_cvt_pk_u8_f32 v125, v125, 3, v122
	v_cvt_pk_u8_f32 v109, v109, 3, v106
	v_mul_f32_e32 v93, 0x437f0000, v93
	v_cvt_pk_u8_f32 v90, v94, 2, v90
	v_mul_f32_e32 v77, 0x437f0000, v77
	v_cvt_pk_u8_f32 v74, v78, 2, v74
	v_cvt_pk_u8_f32 v69, v69, 3, v66
	v_add_co_u32_e32 v66, vcc, s24, v188
	v_mul_f32_e32 v62, 0x437f0000, v62
	v_cvt_pk_u8_f32 v58, v59, 1, v58
	v_mul_f32_e32 v53, 0x437f0000, v53
	v_cvt_pk_u8_f32 v50, v54, 2, v50
	v_mul_f32_e32 v46, 0x437f0000, v46
	v_cvt_pk_u8_f32 v42, v43, 1, v42
	v_mul_f32_e32 v38, 0x437f0000, v38
	v_cvt_pk_u8_f32 v34, v35, 1, v34
	v_pk_mul_f32 v[26:27], v[26:27], s[98:99] op_sel_hi:[1,0]
	v_cvt_pk_u8_f32 v26, v26, 0, 0
	v_pk_mul_f32 v[18:19], v[18:19], s[98:99] op_sel_hi:[1,0]
	v_cvt_pk_u8_f32 v18, v18, 0, 0
	v_pk_mul_f32 v[10:11], v[10:11], s[98:99] op_sel_hi:[1,0]
	v_cvt_pk_u8_f32 v10, v10, 0, 0
	v_pk_mul_f32 v[0:1], v[0:1], s[98:99] op_sel_hi:[1,0]
	v_cvt_pk_u8_f32 v0, v0, 0, 0
	global_store_dwordx2 v[188:189], v[124:125], off
	global_store_dwordx2 v[114:115], v[116:117], off offset:-4096
	global_store_dwordx2 v[114:115], v[108:109], off
	global_store_dwordx2 v[98:99], v[100:101], off offset:-4096
	v_cvt_pk_u8_f32 v93, v93, 3, v90
	v_cvt_pk_u8_f32 v77, v77, 3, v74
	v_addc_co_u32_e32 v67, vcc, 0, v189, vcc
	v_mul_f32_e32 v61, 0x437f0000, v61
	v_cvt_pk_u8_f32 v58, v62, 2, v58
	v_cvt_pk_u8_f32 v53, v53, 3, v50
	v_add_u32_e32 v50, 0, v176
	v_mul_f32_e32 v45, 0x437f0000, v45
	v_cvt_pk_u8_f32 v42, v46, 2, v42
	v_mul_f32_e32 v37, 0x437f0000, v37
	v_cvt_pk_u8_f32 v34, v38, 2, v34
	v_mul_f32_e32 v30, 0x437f0000, v30
	v_cvt_pk_u8_f32 v26, v27, 1, v26
	v_mul_f32_e32 v22, 0x437f0000, v22
	v_cvt_pk_u8_f32 v18, v19, 1, v18
	v_mul_f32_e32 v14, 0x437f0000, v14
	v_cvt_pk_u8_f32 v10, v11, 1, v10
	v_mul_f32_e32 v4, 0x437f0000, v4
	v_cvt_pk_u8_f32 v0, v1, 1, v0
	global_store_dwordx2 v[98:99], v[92:93], off
	global_store_dwordx2 v[82:83], v[84:85], off offset:-4096
	global_store_dwordx2 v[82:83], v[76:77], off
	global_store_dwordx2 v[66:67], v[68:69], off offset:-4096
	v_cvt_pk_u8_f32 v61, v61, 3, v58
	v_add_u32_e32 v50, 0x20000, v50
	v_cvt_pk_u8_f32 v45, v45, 3, v42
	v_cvt_pk_u8_f32 v37, v37, 3, v34
	v_mul_f32_e32 v29, 0x437f0000, v29
	v_cvt_pk_u8_f32 v26, v30, 2, v26
	v_mul_f32_e32 v21, 0x437f0000, v21
	v_cvt_pk_u8_f32 v18, v22, 2, v18
	v_mul_f32_e32 v13, 0x437f0000, v13
	v_cvt_pk_u8_f32 v10, v14, 2, v10
	v_mul_f32_e32 v3, 0x437f0000, v3
	v_cvt_pk_u8_f32 v0, v4, 2, v0
	global_store_dwordx2 v[66:67], v[60:61], off
	ds_write2st64_b64 v50, v[52:53], v[44:45] offset1:8
	ds_write_b64 v50, v[36:37] offset:8192
	v_cvt_pk_u8_f32 v29, v29, 3, v26
	v_cvt_pk_u8_f32 v21, v21, 3, v18
	v_cvt_pk_u8_f32 v13, v13, 3, v10
	v_cvt_pk_u8_f32 v3, v3, 3, v0
	ds_write2st64_b64 v50, v[28:29], v[20:21] offset0:24 offset1:32
	ds_write2st64_b64 v50, v[12:13], v[2:3] offset0:40 offset1:48
